# hy_transpose: loop unrolled by two tiles, two LDS tile buffers (one barrier per tile), loads of tile t+2 in flight
# speedup vs baseline: 1.0037x; 1.0037x over previous
; #define TIDX tid_opaque()
; __device__ __forceinline__ u32x4 zero4() { unsigned z = 0; asm volatile("" : "+v"(z)); return (u32x4){z, z, z, z}; }
; __device__ void hy_transpose_phase(unsigned char* smem, const Params& p, int l) {
;     float* tile = (float*)smem;
;     const bf16_t* uhy = (const bf16_t*)(((unsigned char*)ldp(38)) + OFF_A); bf16_t* hyT = (bf16_t*)(((unsigned char*)ldp(38)) + OFF_B);
;     const float* cw = ((const float*)ldp(7)) + (size_t)l * 3 * HYC; const float* cb = ((const float*)ldp(8)) + (size_t)l * HYC;
;     const int tid = TIDX;
;     const int ntile = (MT / 64) * (HYC / 64);
;     for (int t = blockIdx.x; t < ntile; t += gridDim.x) {
;         const int cblk = t % (HYC / 64), rblk = t / (HYC / 64); const int b = rblk >> 5, t0 = (rblk & 31) * 64, c0 = cblk * 64;
;         __syncthreads();
;         for (int e = tid; e < 66 * 8; e += 512) { const int rr = e >> 3, c8 = e & 7; const int tt = t0 - 1 + rr;
;             u32x4 v = zero4();
;             if (tt >= 0 && tt < SEQ) v = *(const u32x4*)(uhy + ((size_t)b * SEQ + tt) * HYC + c0 + c8 * 8);
.LBB0_248:
	s_or_b64 exec, exec, s[6:7]
	s_and_b32 s5, s30, 0xffff
	s_cmp_lg_u32 s40, -1
	s_cselect_b32 s0, s40, 0
	s_cselect_b32 s1, s41, 0
	v_mov_b64_e32 v[0:1], s[0:1]
	s_add_i32 s0, 0, 0x23e38
	s_cmp_lg_u32 s0, -1
	s_cselect_b32 s0, s0, 0
	s_cselect_b32 s1, s41, 0
	v_mov_b32_e32 v4, s0
	s_add_i32 s0, 0, 0x23e40
	s_cmp_lg_u32 s0, -1
	v_mov_b32_e32 v5, s1
	s_cselect_b32 s0, s0, 0
	s_cselect_b32 s1, s41, 0
	v_mov_b32_e32 v6, s0
	v_mov_b32_e32 v7, s1
	flat_load_dwordx2 v[2:3], v[0:1] sc0 sc1
	s_waitcnt vmcnt(0)
	flat_load_dwordx2 v[0:1], v[0:1] sc0 sc1
	s_waitcnt vmcnt(0)
	v_readlane_b32 s0, v254, 46
	flat_load_dwordx2 v[4:5], v[4:5] sc0 sc1
	s_waitcnt vmcnt(0)
	v_readlane_b32 s1, v254, 47
	flat_load_dwordx2 v[8:9], v[6:7] sc0 sc1
	s_waitcnt vmcnt(0)
	v_mov_b32_e32 v7, v234
	s_andn2_b64 vcc, exec, s[0:1]
	s_waitcnt lgkmcnt(0)
	v_readfirstlane_b32 s13, v3
	v_readfirstlane_b32 s12, v2
	v_readfirstlane_b32 s7, v1
	v_readfirstlane_b32 s6, v0
	v_readfirstlane_b32 s1, v5
	v_readfirstlane_b32 s8, v4
	v_readfirstlane_b32 s0, v9
	v_readfirstlane_b32 s10, v8
	s_cbranch_vccnz .LBB0_259
	s_add_u32 s6, s6, 0x12c00000
	s_mul_i32 s9, s5, 0x4800
	s_addc_u32 s7, s7, 0
	s_add_u32 s8, s8, s9
	v_and_b32_e32 v6, 7, v7
	s_mul_i32 s11, s5, 0x1800
	s_addc_u32 s9, s1, 0
	v_lshlrev_b32_e32 v0, 3, v7
	v_lshlrev_b32_e32 v184, 4, v6
	s_add_u32 s10, s10, s11
	v_ashrrev_i32_e32 v10, 3, v7
	v_and_b32_e32 v0, 56, v0
	v_lshl_add_u64 v[2:3], s[12:13], 0, v[184:185]
	s_mov_b64 s[12:13], 0x7c00000
	s_addc_u32 s11, s0, 0
	s_movk_i32 s0, 0x20f
	v_lshl_add_u32 v1, v10, 2, 0
	v_lshl_add_u64 v[4:5], v[2:3], 0, s[12:13]
	v_mul_u32_u24_e32 v2, 0x104, v0
	v_cmp_lt_i32_e64 s[0:1], s0, v7
	v_lshl_add_u32 v6, v6, 5, 0
	v_add_u32_e32 v11, v1, v2
	v_lshlrev_b32_e32 v184, 1, v0
	s_mov_b32 s15, s2
	v_readfirstlane_b32 s31, v7
	v_add_u32_e32 v66, 0x4400, v11
	s_mov_b32 s98, s2
	s_mul_hi_i32 s99, s98, 0x2aaaaaab
	s_lshr_b32 s100, s99, 31
	s_ashr_i32 s99, s99, 2
	s_add_i32 s99, s99, s100
	s_mul_i32 s100, s99, 24
	s_sub_i32 s100, s98, s100
	s_lshl_b32 s100, s100, 7
	s_lshl_b32 s101, s99, 6
	s_and_b32 s101, s101, 0x7c0
	s_add_i32 s101, s101, -1
	s_ashr_i32 s99, s99, 5
	s_lshl_b32 s99, s99, 11
	v_add_u32_e32 v44, s101, v10
	v_add_u32_e32 v45, s99, v44
	v_mul_u32_u24_e32 v45, 0xc00, v45
	v_add_u32_e32 v46, s100, v45
	v_mov_b32_e32 v47, 0
	v_mov_b32_e32 v36, 0
	v_mov_b32_e32 v37, 0
	v_mov_b32_e32 v38, 0
	v_mov_b32_e32 v39, 0
	v_lshl_add_u64 v[46:47], v[4:5], 0, v[46:47]
	v_cmp_gt_u32_e32 vcc, 0x800, v44
	s_and_saveexec_b64 s[28:29], vcc
	global_load_dwordx4 v[36:39], v[46:47], off
	s_mov_b64 exec, s[28:29]
	s_cmp_lt_u32 s31, 64
	s_cbranch_scc0 .Lhy3_p2_pa
	v_add_u32_e32 v44, 64, v44
	v_add_u32_e32 v45, s99, v44
	v_mul_u32_u24_e32 v45, 0xc00, v45
	v_add_u32_e32 v46, s100, v45
	v_mov_b32_e32 v47, 0
	v_mov_b32_e32 v40, 0
	v_mov_b32_e32 v41, 0
	v_mov_b32_e32 v42, 0
	v_mov_b32_e32 v43, 0
	v_lshl_add_u64 v[46:47], v[4:5], 0, v[46:47]
	v_cmp_gt_u32_e32 vcc, 0x800, v44
	v_cmp_gt_u32_e64 s[34:35], 16, v7
	s_and_b64 vcc, vcc, s[34:35]
	s_and_saveexec_b64 s[28:29], vcc
	global_load_dwordx4 v[40:43], v[46:47], off
	s_mov_b64 exec, s[28:29]
.Lhy3_p2_pa:
	s_add_i32 s98, s15, s14
	s_cmpk_gt_i32 s98, 0x2fff
	s_cbranch_scc1 .Lhy3_pro1
	s_mul_hi_i32 s99, s98, 0x2aaaaaab
	s_lshr_b32 s100, s99, 31
	s_ashr_i32 s99, s99, 2
	s_add_i32 s99, s99, s100
	s_mul_i32 s100, s99, 24
	s_sub_i32 s100, s98, s100
	s_lshl_b32 s100, s100, 7
	s_lshl_b32 s101, s99, 6
	s_and_b32 s101, s101, 0x7c0
	s_add_i32 s101, s101, -1
	s_ashr_i32 s99, s99, 5
	s_lshl_b32 s99, s99, 11
	v_add_u32_e32 v44, s101, v10
	v_add_u32_e32 v45, s99, v44
	v_mul_u32_u24_e32 v45, 0xc00, v45
	v_add_u32_e32 v46, s100, v45
	v_mov_b32_e32 v47, 0
	v_mov_b32_e32 v58, 0
	v_mov_b32_e32 v59, 0
	v_mov_b32_e32 v60, 0
	v_mov_b32_e32 v61, 0
	v_lshl_add_u64 v[46:47], v[4:5], 0, v[46:47]
	v_cmp_gt_u32_e32 vcc, 0x800, v44
	s_and_saveexec_b64 s[28:29], vcc
	global_load_dwordx4 v[58:61], v[46:47], off
	s_mov_b64 exec, s[28:29]
	s_cmp_lt_u32 s31, 64
	s_cbranch_scc0 .Lhy3_p2_pb
	v_add_u32_e32 v44, 64, v44
	v_add_u32_e32 v45, s99, v44
	v_mul_u32_u24_e32 v45, 0xc00, v45
	v_add_u32_e32 v46, s100, v45
	v_mov_b32_e32 v47, 0
	v_mov_b32_e32 v62, 0
	v_mov_b32_e32 v63, 0
	v_mov_b32_e32 v64, 0
	v_mov_b32_e32 v65, 0
	v_lshl_add_u64 v[46:47], v[4:5], 0, v[46:47]
	v_cmp_gt_u32_e32 vcc, 0x800, v44
	v_cmp_gt_u32_e64 s[34:35], 16, v7
	s_and_b64 vcc, vcc, s[34:35]
	s_and_saveexec_b64 s[28:29], vcc
	global_load_dwordx4 v[62:65], v[46:47], off
	s_mov_b64 exec, s[28:29]
.Lhy3_p2_pb:
	s_waitcnt vmcnt(1)
	s_branch .Lhy3_pro2

; __device__ __forceinline__ u32x4 zero4() { unsigned z = 0; asm volatile("" : "+v"(z)); return (u32x4){z, z, z, z}; }
; __device__ __forceinline__ float lo_bf(unsigned w) { return __uint_as_float(w << 16); }
; __device__ __forceinline__ float hi_bf(unsigned w) { return __uint_as_float(w & 0xffff0000u); }
; __device__ void hy_transpose_phase(unsigned char* smem, const Params& p, int l) {
;     ...
;     for (int t = blockIdx.x; t < ntile; t += gridDim.x) {
;         const int cblk = t % (HYC / 64), rblk = t / (HYC / 64); const int b = rblk >> 5, t0 = (rblk & 31) * 64, c0 = cblk * 64;
;         __syncthreads();
;         for (int e = tid; e < 66 * 8; e += 512) { const int rr = e >> 3, c8 = e & 7; const int tt = t0 - 1 + rr;
;             u32x4 v = zero4();
;             if (tt >= 0 && tt < SEQ) v = *(const u32x4*)(uhy + ((size_t)b * SEQ + tt) * HYC + c0 + c8 * 8);
;             float* d = tile + rr * 65 + c8 * 8;
;             d[0] = lo_bf(v.x); d[1] = hi_bf(v.x); d[2] = lo_bf(v.y); d[3] = hi_bf(v.y); d[4] = lo_bf(v.z); d[5] = hi_bf(v.z); d[6] = lo_bf(v.w); d[7] = hi_bf(v.w); }
;         __syncthreads();
;         { const int cc = tid >> 3, t8 = tid & 7, c = c0 + cc; const float w0 = cw[c], w1 = cw[HYC + c], w2 = cw[2 * HYC + c], bb = cb[c];
;           float x[10];
; #pragma unroll
;           for (int i = 0; i < 10; ++i) x[i] = tile[(t8 * 8 + i) * 65 + cc];
.Lhy3_top_0:
	s_mul_hi_i32 s12, s15, 0x2aaaaaab
	s_lshr_b32 s13, s12, 31
	s_ashr_i32 s20, s12, 2
	s_add_i32 s20, s20, s13
	s_ashr_i32 s12, s20, 5
	s_ashr_i32 s13, s12, 31
	s_mul_i32 s16, s20, 24
	s_sub_i32 s16, s15, s16
	s_lshl_b32 s17, s20, 6
	s_and_b32 s24, s17, 0x7c0
	s_lshl_b32 s16, s16, 6
	v_add_u32_e32 v48, s16, v10
	v_ashrrev_i32_e32 v49, 31, v48
	v_lshlrev_b64 v[48:49], 2, v[48:49]
	v_lshl_add_u64 v[46:47], s[8:9], 0, v[48:49]
	s_mov_b64 s[22:23], 0x1800
	global_load_dword v50, v[46:47], off
	v_lshl_add_u64 v[44:45], v[46:47], 0, s[22:23]
	s_mov_b64 s[22:23], 0x3000
	global_load_dword v52, v[44:45], off
	v_lshl_add_u64 v[44:45], v[46:47], 0, s[22:23]
	global_load_dword v54, v[44:45], off
	v_lshl_add_u64 v[44:45], s[10:11], 0, v[48:49]
	global_load_dword v56, v[44:45], off
	s_waitcnt vmcnt(10)
	v_mul_u32_u24_e32 v14, 0x104, v10
	v_add_u32_e32 v14, v14, v6
	v_lshlrev_b32_e32 v13, 16, v36
	v_and_b32_e32 v0, 0xffff0000, v36
	ds_write2_b32 v14, v13, v0 offset0:0 offset1:1
	v_lshlrev_b32_e32 v13, 16, v37
	v_and_b32_e32 v0, 0xffff0000, v37
	ds_write2_b32 v14, v13, v0 offset0:2 offset1:3
	v_lshlrev_b32_e32 v13, 16, v38
	v_and_b32_e32 v0, 0xffff0000, v38
	ds_write2_b32 v14, v13, v0 offset0:4 offset1:5
	v_lshlrev_b32_e32 v13, 16, v39
	v_and_b32_e32 v0, 0xffff0000, v39
	ds_write2_b32 v14, v13, v0 offset0:6 offset1:7
	v_cmp_gt_u32_e32 vcc, 16, v7
	s_and_saveexec_b64 s[28:29], vcc
	v_add_u32_e32 v14, 0x4100, v14
	v_lshlrev_b32_e32 v13, 16, v40
	v_and_b32_e32 v0, 0xffff0000, v40
	ds_write2_b32 v14, v13, v0 offset0:0 offset1:1
	v_lshlrev_b32_e32 v13, 16, v41
	v_and_b32_e32 v0, 0xffff0000, v41
	ds_write2_b32 v14, v13, v0 offset0:2 offset1:3
	v_lshlrev_b32_e32 v13, 16, v42
	v_and_b32_e32 v0, 0xffff0000, v42
	ds_write2_b32 v14, v13, v0 offset0:4 offset1:5
	v_lshlrev_b32_e32 v13, 16, v43
	v_and_b32_e32 v0, 0xffff0000, v43
	ds_write2_b32 v14, v13, v0 offset0:6 offset1:7
	s_mov_b64 exec, s[28:29]
	s_lshl_b32 s98, s14, 1
	s_add_i32 s98, s98, s15
	s_cmpk_gt_i32 s98, 0x2fff
	s_cbranch_scc1 .Lhy3_nopf_0
	s_mul_hi_i32 s99, s98, 0x2aaaaaab
	s_lshr_b32 s100, s99, 31
	s_ashr_i32 s99, s99, 2
	s_add_i32 s99, s99, s100
	s_mul_i32 s100, s99, 24
	s_sub_i32 s100, s98, s100
	s_lshl_b32 s100, s100, 7
	s_lshl_b32 s101, s99, 6
	s_and_b32 s101, s101, 0x7c0
	s_add_i32 s101, s101, -1
	s_ashr_i32 s99, s99, 5
	s_lshl_b32 s99, s99, 11
	v_add_u32_e32 v44, s101, v10
	v_add_u32_e32 v45, s99, v44
	v_mul_u32_u24_e32 v45, 0xc00, v45
	v_add_u32_e32 v46, s100, v45
	v_mov_b32_e32 v47, 0
	v_mov_b32_e32 v36, 0
	v_mov_b32_e32 v37, 0
	v_mov_b32_e32 v38, 0
	v_mov_b32_e32 v39, 0
	v_lshl_add_u64 v[46:47], v[4:5], 0, v[46:47]
	v_cmp_gt_u32_e32 vcc, 0x800, v44
	s_and_saveexec_b64 s[28:29], vcc
	global_load_dwordx4 v[36:39], v[46:47], off
	s_mov_b64 exec, s[28:29]
	s_cmp_lt_u32 s31, 64
	s_cbranch_scc0 .Lhy3_p2_l0
	v_add_u32_e32 v44, 64, v44
	v_add_u32_e32 v45, s99, v44
	v_mul_u32_u24_e32 v45, 0xc00, v45
	v_add_u32_e32 v46, s100, v45
	v_mov_b32_e32 v47, 0
	v_mov_b32_e32 v40, 0
	v_mov_b32_e32 v41, 0
	v_mov_b32_e32 v42, 0
	v_mov_b32_e32 v43, 0
	v_lshl_add_u64 v[46:47], v[4:5], 0, v[46:47]
	v_cmp_gt_u32_e32 vcc, 0x800, v44
	v_cmp_gt_u32_e64 s[34:35], 16, v7
	s_and_b64 vcc, vcc, s[34:35]
	s_and_saveexec_b64 s[28:29], vcc
	global_load_dwordx4 v[40:43], v[46:47], off
	s_mov_b64 exec, s[28:29]
.Lhy3_p2_l0:
	s_branch .Lhy3_cmp_0
.Lhy3_nopf_0:
	s_waitcnt vmcnt(0)
.Lhy3_cmp_0:
	v_mov_b64_e32 v[0:1], s[12:13]
	v_add_u32_e32 v2, s16, v10
	v_ashrrev_i32_e32 v3, 31, v2
	s_waitcnt lgkmcnt(0)
	s_barrier
	v_add_u32_e32 v9, 0x400, v11
	ds_read2_b32 v[18:19], v11 offset1:65
	ds_read2_b32 v[20:21], v11 offset0:130 offset1:195
	v_add_u32_e32 v13, 0x800, v11
	ds_read2_b32 v[22:23], v9 offset0:4 offset1:69
	ds_read2_b32 v[24:25], v9 offset0:134 offset1:199
	ds_read2_b32 v[26:27], v13 offset0:8 offset1:73
	v_lshlrev_b64 v[2:3], 16, v[2:3]
	v_lshlrev_b64 v[0:1], 12, v[0:1]
	v_lshl_add_u64 v[2:3], s[6:7], 0, v[2:3]
	s_lshl_b32 s24, s24, 1
	v_lshl_add_u64 v[0:1], v[2:3], 0, v[0:1]
	s_waitcnt lgkmcnt(4)
	v_mov_b32_e32 v2, v19
	s_waitcnt lgkmcnt(3)
	v_mov_b32_e32 v3, v20
	v_mov_b32_e32 v28, v21
	v_lshl_add_u64 v[0:1], v[0:1], 0, s[24:25]
	s_waitcnt lgkmcnt(2)
	v_mov_b32_e32 v29, v22
	v_mov_b32_e32 v30, v23
	s_waitcnt lgkmcnt(1)
	v_mov_b32_e32 v31, v24
	v_mov_b32_e32 v32, v25
	s_waitcnt lgkmcnt(0)
	v_mov_b32_e32 v33, v26
	v_lshl_add_u64 v[34:35], v[0:1], 0, v[184:185]
	s_cmp_lt_u32 s31, 64
	s_cbranch_scc1 .Lhy3_w0_0
	s_waitcnt vmcnt(1)
	s_branch .Lhy3_wj_0

; __device__ __forceinline__ u32x4 zero4() { unsigned z = 0; asm volatile("" : "+v"(z)); return (u32x4){z, z, z, z}; }
; __device__ __forceinline__ float lo_bf(unsigned w) { return __uint_as_float(w << 16); }
; __device__ __forceinline__ float hi_bf(unsigned w) { return __uint_as_float(w & 0xffff0000u); }
; __device__ void hy_transpose_phase(unsigned char* smem, const Params& p, int l) {
;     ...
;     for (int t = blockIdx.x; t < ntile; t += gridDim.x) {
;         const int cblk = t % (HYC / 64), rblk = t / (HYC / 64); const int b = rblk >> 5, t0 = (rblk & 31) * 64, c0 = cblk * 64;
;         __syncthreads();
;         for (int e = tid; e < 66 * 8; e += 512) { const int rr = e >> 3, c8 = e & 7; const int tt = t0 - 1 + rr;
;             u32x4 v = zero4();
;             if (tt >= 0 && tt < SEQ) v = *(const u32x4*)(uhy + ((size_t)b * SEQ + tt) * HYC + c0 + c8 * 8);
;             float* d = tile + rr * 65 + c8 * 8;
;             d[0] = lo_bf(v.x); d[1] = hi_bf(v.x); d[2] = lo_bf(v.y); d[3] = hi_bf(v.y); d[4] = lo_bf(v.z); d[5] = hi_bf(v.z); d[6] = lo_bf(v.w); d[7] = hi_bf(v.w); }
;         __syncthreads();
;         { const int cc = tid >> 3, t8 = tid & 7, c = c0 + cc; const float w0 = cw[c], w1 = cw[HYC + c], w2 = cw[2 * HYC + c], bb = cb[c];
;           float x[10];
; #pragma unroll
;           for (int i = 0; i < 10; ++i) x[i] = tile[(t8 * 8 + i) * 65 + cc];
.Lhy3_top_1:
	s_mul_hi_i32 s12, s15, 0x2aaaaaab
	s_lshr_b32 s13, s12, 31
	s_ashr_i32 s20, s12, 2
	s_add_i32 s20, s20, s13
	s_ashr_i32 s12, s20, 5
	s_ashr_i32 s13, s12, 31
	s_mul_i32 s16, s20, 24
	s_sub_i32 s16, s15, s16
	s_lshl_b32 s17, s20, 6
	s_and_b32 s24, s17, 0x7c0
	s_lshl_b32 s16, s16, 6
	v_add_u32_e32 v48, s16, v10
	v_ashrrev_i32_e32 v49, 31, v48
	v_lshlrev_b64 v[48:49], 2, v[48:49]
	v_lshl_add_u64 v[46:47], s[8:9], 0, v[48:49]
	s_mov_b64 s[22:23], 0x1800
	global_load_dword v50, v[46:47], off
	v_lshl_add_u64 v[44:45], v[46:47], 0, s[22:23]
	s_mov_b64 s[22:23], 0x3000
	global_load_dword v52, v[44:45], off
	v_lshl_add_u64 v[44:45], v[46:47], 0, s[22:23]
	global_load_dword v54, v[44:45], off
	v_lshl_add_u64 v[44:45], s[10:11], 0, v[48:49]
	global_load_dword v56, v[44:45], off
	s_waitcnt vmcnt(10)
	v_mul_u32_u24_e32 v14, 0x104, v10
	v_add_u32_e32 v14, v14, v6
	v_add_u32_e32 v14, 0x4400, v14
	v_lshlrev_b32_e32 v13, 16, v58
	v_and_b32_e32 v0, 0xffff0000, v58
	ds_write2_b32 v14, v13, v0 offset0:0 offset1:1
	v_lshlrev_b32_e32 v13, 16, v59
	v_and_b32_e32 v0, 0xffff0000, v59
	ds_write2_b32 v14, v13, v0 offset0:2 offset1:3
	v_lshlrev_b32_e32 v13, 16, v60
	v_and_b32_e32 v0, 0xffff0000, v60
	ds_write2_b32 v14, v13, v0 offset0:4 offset1:5
	v_lshlrev_b32_e32 v13, 16, v61
	v_and_b32_e32 v0, 0xffff0000, v61
	ds_write2_b32 v14, v13, v0 offset0:6 offset1:7
	v_cmp_gt_u32_e32 vcc, 16, v7
	s_and_saveexec_b64 s[28:29], vcc
	v_add_u32_e32 v14, 0x4100, v14
	v_lshlrev_b32_e32 v13, 16, v62
	v_and_b32_e32 v0, 0xffff0000, v62
	ds_write2_b32 v14, v13, v0 offset0:0 offset1:1
	v_lshlrev_b32_e32 v13, 16, v63
	v_and_b32_e32 v0, 0xffff0000, v63
	ds_write2_b32 v14, v13, v0 offset0:2 offset1:3
	v_lshlrev_b32_e32 v13, 16, v64
	v_and_b32_e32 v0, 0xffff0000, v64
	ds_write2_b32 v14, v13, v0 offset0:4 offset1:5
	v_lshlrev_b32_e32 v13, 16, v65
	v_and_b32_e32 v0, 0xffff0000, v65
	ds_write2_b32 v14, v13, v0 offset0:6 offset1:7
	s_mov_b64 exec, s[28:29]
	s_lshl_b32 s98, s14, 1
	s_add_i32 s98, s98, s15
	s_cmpk_gt_i32 s98, 0x2fff
	s_cbranch_scc1 .Lhy3_nopf_1
	s_mul_hi_i32 s99, s98, 0x2aaaaaab
	s_lshr_b32 s100, s99, 31
	s_ashr_i32 s99, s99, 2
	s_add_i32 s99, s99, s100
	s_mul_i32 s100, s99, 24
	s_sub_i32 s100, s98, s100
	s_lshl_b32 s100, s100, 7
	s_lshl_b32 s101, s99, 6
	s_and_b32 s101, s101, 0x7c0
	s_add_i32 s101, s101, -1
	s_ashr_i32 s99, s99, 5
	s_lshl_b32 s99, s99, 11
	v_add_u32_e32 v44, s101, v10
	v_add_u32_e32 v45, s99, v44
	v_mul_u32_u24_e32 v45, 0xc00, v45
	v_add_u32_e32 v46, s100, v45
	v_mov_b32_e32 v47, 0
	v_mov_b32_e32 v58, 0
	v_mov_b32_e32 v59, 0
	v_mov_b32_e32 v60, 0
	v_mov_b32_e32 v61, 0
	v_lshl_add_u64 v[46:47], v[4:5], 0, v[46:47]
	v_cmp_gt_u32_e32 vcc, 0x800, v44
	s_and_saveexec_b64 s[28:29], vcc
	global_load_dwordx4 v[58:61], v[46:47], off
	s_mov_b64 exec, s[28:29]
	s_cmp_lt_u32 s31, 64
	s_cbranch_scc0 .Lhy3_p2_l1
	v_add_u32_e32 v44, 64, v44
	v_add_u32_e32 v45, s99, v44
	v_mul_u32_u24_e32 v45, 0xc00, v45
	v_add_u32_e32 v46, s100, v45
	v_mov_b32_e32 v47, 0
	v_mov_b32_e32 v62, 0
	v_mov_b32_e32 v63, 0
	v_mov_b32_e32 v64, 0
	v_mov_b32_e32 v65, 0
	v_lshl_add_u64 v[46:47], v[4:5], 0, v[46:47]
	v_cmp_gt_u32_e32 vcc, 0x800, v44
	v_cmp_gt_u32_e64 s[34:35], 16, v7
	s_and_b64 vcc, vcc, s[34:35]
	s_and_saveexec_b64 s[28:29], vcc
	global_load_dwordx4 v[62:65], v[46:47], off
	s_mov_b64 exec, s[28:29]
.Lhy3_p2_l1:
	s_branch .Lhy3_cmp_1
.Lhy3_nopf_1:
	s_waitcnt vmcnt(0)
.Lhy3_cmp_1:
	v_mov_b64_e32 v[0:1], s[12:13]
	v_add_u32_e32 v2, s16, v10
	v_ashrrev_i32_e32 v3, 31, v2
	s_waitcnt lgkmcnt(0)
	s_barrier
	v_add_u32_e32 v9, 0x400, v66
	ds_read2_b32 v[18:19], v66 offset1:65
	ds_read2_b32 v[20:21], v66 offset0:130 offset1:195
	v_add_u32_e32 v13, 0x800, v66
	ds_read2_b32 v[22:23], v9 offset0:4 offset1:69
	ds_read2_b32 v[24:25], v9 offset0:134 offset1:199
	ds_read2_b32 v[26:27], v13 offset0:8 offset1:73
	v_lshlrev_b64 v[2:3], 16, v[2:3]
	v_lshlrev_b64 v[0:1], 12, v[0:1]
	v_lshl_add_u64 v[2:3], s[6:7], 0, v[2:3]
	s_lshl_b32 s24, s24, 1
	v_lshl_add_u64 v[0:1], v[2:3], 0, v[0:1]
	s_waitcnt lgkmcnt(4)
	v_mov_b32_e32 v2, v19
	s_waitcnt lgkmcnt(3)
	v_mov_b32_e32 v3, v20
	v_mov_b32_e32 v28, v21
	v_lshl_add_u64 v[0:1], v[0:1], 0, s[24:25]
	s_waitcnt lgkmcnt(2)
	v_mov_b32_e32 v29, v22
	v_mov_b32_e32 v30, v23
	s_waitcnt lgkmcnt(1)
	v_mov_b32_e32 v31, v24
	v_mov_b32_e32 v32, v25
	s_waitcnt lgkmcnt(0)
	v_mov_b32_e32 v33, v26
	v_lshl_add_u64 v[34:35], v[0:1], 0, v[184:185]
	s_cmp_lt_u32 s31, 64
	s_cbranch_scc1 .Lhy3_w0_1
	s_waitcnt vmcnt(1)
	s_branch .Lhy3_wj_1

; __device__ __forceinline__ unsigned cvt_pk_bf16(float lo, float hi) { const f32x2_t v = {lo, hi}; const bf16x2_t b = __builtin_convertvector(v, bf16x2_t); return __builtin_bit_cast(unsigned, b); }
; __device__ void hy_transpose_phase(unsigned char* smem, const Params& p, int l) {
;     ...
;         { const int cc = tid >> 3, t8 = tid & 7, c = c0 + cc; const float w0 = cw[c], w1 = cw[HYC + c], w2 = cw[2 * HYC + c], bb = cb[c];
;           float x[10];
; #pragma unroll
;           for (int i = 0; i < 10; ++i) x[i] = tile[(t8 * 8 + i) * 65 + cc];
;           float o[8];
; #pragma unroll
;           for (int i = 0; i < 8; ++i) o[i] = w0 * x[i] + w1 * x[i + 1] + w2 * x[i + 2] + bb;
;           u32x4 w; w.x = cvt_pk_bf16(o[0], o[1]); w.y = cvt_pk_bf16(o[2], o[3]); w.z = cvt_pk_bf16(o[4], o[5]); w.w = cvt_pk_bf16(o[6], o[7]);
;           *(u32x4*)(hyT + ((size_t)c * NB + b) * SEQ + t0 + t8 * 8) = w; }
.Lhy3_wj_1:
	s_add_i32 s15, s15, s14
	s_cmpk_gt_i32 s15, 0x2fff
	v_pk_mul_f32 v[0:1], v[52:53], v[2:3] op_sel_hi:[0,1]
	v_pk_mul_f32 v[2:3], v[52:53], v[28:29] op_sel_hi:[0,1]
	v_pk_mul_f32 v[28:29], v[52:53], v[30:31] op_sel_hi:[0,1]
	v_pk_mul_f32 v[14:15], v[52:53], v[32:33] op_sel_hi:[0,1]
	v_pk_fma_f32 v[0:1], v[50:51], v[18:19], v[0:1] op_sel_hi:[0,1,1]
	v_pk_fma_f32 v[2:3], v[50:51], v[20:21], v[2:3] op_sel_hi:[0,1,1]
	v_pk_fma_f32 v[18:19], v[50:51], v[22:23], v[28:29] op_sel_hi:[0,1,1]
	v_pk_fma_f32 v[12:13], v[50:51], v[24:25], v[14:15] op_sel_hi:[0,1,1]
	v_pk_fma_f32 v[0:1], v[54:55], v[20:21], v[0:1] op_sel_hi:[0,1,1]
	v_pk_fma_f32 v[2:3], v[54:55], v[22:23], v[2:3] op_sel_hi:[0,1,1]
	v_pk_fma_f32 v[14:15], v[54:55], v[24:25], v[18:19] op_sel_hi:[0,1,1]
	v_pk_fma_f32 v[12:13], v[54:55], v[26:27], v[12:13] op_sel_hi:[0,1,1]
	v_pk_add_f32 v[0:1], v[56:57], v[0:1] op_sel_hi:[0,1]
	v_pk_add_f32 v[2:3], v[56:57], v[2:3] op_sel_hi:[0,1]
	v_pk_add_f32 v[14:15], v[56:57], v[14:15] op_sel_hi:[0,1]
	v_pk_add_f32 v[8:9], v[56:57], v[12:13] op_sel_hi:[0,1]
	v_cvt_pk_bf16_f32 v0, v0, v1
	v_cvt_pk_bf16_f32 v1, v2, v3
	v_cvt_pk_bf16_f32 v2, v14, v15
	v_cvt_pk_bf16_f32 v3, v8, v9
	global_store_dwordx4 v[34:35], v[0:3], off
	s_cbranch_scc1 .LBB0_259
	s_branch .Lhy3_top_0
